# GEMM phase prologues: K-tile 1 LDS-DMA pieces issued before the first wait+barrier (both K-tiles in flight together); on hoists + paired poll
# baseline (speedup 1.0000x reference)
.LBB0_105:
	v_mov_b32_e32 v165, v27
	v_lshl_add_u64 v[58:59], s[86:87], 0, v[164:165]
	v_mov_b32_e32 v161, v27
	v_lshl_add_u64 v[84:85], s[86:87], 0, v[160:161]
	s_add_i32 m0, s17, 0x18000
	v_lshl_add_u64 v[58:59], v[58:59], 0, s[82:83]
	v_readlane_b32 s26, v251, 55
	v_mov_b32_e32 v167, v27
	global_load_lds_dwordx4 v[58:59], off
	v_lshl_add_u64 v[58:59], v[84:85], 0, s[82:83]
	s_add_i32 m0, s17, 0x1a000
	v_readlane_b32 s27, v251, 56
	s_add_i32 s22, s17, 0x8000
	v_mov_b32_e32 v163, v27
	global_load_lds_dwordx4 v[58:59], off
	v_lshl_add_u64 v[58:59], s[26:27], 0, v[166:167]
	s_mov_b32 m0, s22
	s_add_i32 s80, s17, 0xa000
	global_load_lds_dwordx4 v[58:59], off
	v_lshl_add_u64 v[58:59], s[26:27], 0, v[162:163]
	s_mov_b32 m0, s80
	s_and_b32 s1, s1, 3
	global_load_lds_dwordx4 v[58:59], off
	s_add_i32 m0, s17, 0x1c000
	v_lshl_add_u64 v[58:59], s[52:53], 0, v[164:165]
	global_load_lds_dwordx4 v[58:59], off
	v_lshl_add_u64 v[58:59], s[52:53], 0, v[160:161]
	s_add_i32 m0, s17, 0x1e000
	v_mul_lo_u32 v26, v26, s7
	global_load_lds_dwordx4 v[58:59], off
	s_waitcnt vmcnt(8)
	s_barrier
	v_bfe_u32 v59, v37, 4, 2
	v_and_b32_e32 v58, 15, v37
	v_lshlrev_b32_e32 v185, 4, v59
	v_lshlrev_b32_e32 v37, 2, v37
	v_lshl_or_b32 v184, s11, 6, v58
	v_lshl_or_b32 v58, v58, 6, v185
	s_lshl_b32 s11, s11, 13
	v_and_b32_e32 v37, 32, v37
	v_bitop3_b32 v84, v58, s11, v37 bitop3:0xde
	s_lshl_b32 s11, s1, 12
	v_bitop3_b32 v186, v58, s11, v37 bitop3:0xde
	s_cmpk_lt_u32 s0, 0x100
	v_lshrrev_b32_e32 v37, 1, v56
	v_mul_lo_u32 v58, v39, s7
	s_mov_b32 s11, 0x2c000
	s_cselect_b64 s[60:61], -1, 0
	v_cmp_eq_u32_e64 s[38:39], 0, v59
	s_lshl_b32 s26, s1, 1
	v_lshl_or_b32 v187, s1, 6, v185
	v_mad_u64_u32 v[58:59], s[0:1], v37, s11, v[58:59]
	v_and_b32_e32 v37, 1, v56
	v_lshl_or_b32 v37, v37, 6, v58
	v_lshl_add_u32 v176, v57, 1, v37
	v_lshrrev_b32_e32 v37, 1, v36
	v_mad_u64_u32 v[56:57], s[0:1], v37, s11, v[26:27]
	s_waitcnt vmcnt(6)
	v_and_b32_e32 v26, 1, v36
	v_readlane_b32 s0, v251, 36
	v_lshl_or_b32 v26, v26, 6, v56
	s_mov_b32 s94, s0
	v_readlane_b32 s0, v251, 34
	v_readlane_b32 s78, v251, 37
	s_mov_b32 s81, 0
	s_orn2_b32 s26, s26, 47
	v_mov_b32_e32 v177, v27
	v_lshl_add_u32 v178, v38, 1, v26
	v_mov_b32_e32 v179, v27
	v_add_u32_e32 v188, 0, v84
	v_readlane_b32 s31, v251, 35
	s_mov_b32 s30, s0
	s_mov_b64 s[76:77], s[86:87]
	v_readlane_b32 s79, v251, 38
	s_barrier
	s_branch .LBB0_108

.LBB0_202:
	v_mov_b32_e32 v159, v27
	v_lshl_add_u64 v[10:11], s[36:37], 0, v[158:159]
	v_mov_b32_e32 v163, v27
	v_lshl_add_u64 v[12:13], s[36:37], 0, v[162:163]
	v_mov_b32_e32 v157, v27
	s_add_i32 m0, s11, 0x18000
	v_lshl_add_u64 v[10:11], v[10:11], 0, s[82:83]
	v_lshl_add_u64 v[14:15], s[70:71], 0, v[156:157]
	v_mov_b32_e32 v161, v27
	global_load_lds_dwordx4 v[10:11], off
	v_lshl_add_u64 v[10:11], v[12:13], 0, s[82:83]
	s_add_i32 m0, s11, 0x1a000
	s_add_i32 s26, s11, 0x8000
	v_lshl_add_u64 v[16:17], s[70:71], 0, v[160:161]
	global_load_lds_dwordx4 v[10:11], off
	v_lshl_add_u64 v[10:11], v[14:15], 0, s[82:83]
	s_mov_b32 m0, s26
	s_add_i32 s27, s11, 0xa000
	global_load_lds_dwordx4 v[10:11], off
	v_lshl_add_u64 v[10:11], v[16:17], 0, s[82:83]
	s_mov_b32 m0, s27
	v_and_b32_e32 v9, 15, v2
	global_load_lds_dwordx4 v[10:11], off
	s_add_i32 m0, s11, 0x1c000
	v_lshl_add_u64 v[10:11], s[28:29], 0, v[158:159]
	global_load_lds_dwordx4 v[10:11], off
	v_lshl_add_u64 v[10:11], s[28:29], 0, v[162:163]
	s_add_i32 m0, s11, 0x1e000
	v_and_b32_e32 v187, 48, v2
	global_load_lds_dwordx4 v[10:11], off
	s_waitcnt vmcnt(8)
	s_barrier
	v_lshlrev_b32_e32 v10, 2, v2
	v_lshlrev_b32_e32 v2, 3, v2
	v_and_b32_e32 v164, 0x1f8, v2
	v_lshlrev_b32_e32 v2, 13, v3
	v_and_b32_e32 v2, 0xffffc000, v2
	v_lshl_add_u32 v2, v4, 10, v2
	v_and_b32_e32 v3, 1, v3
	s_and_b32 s39, s31, 3
	v_lshl_or_b32 v188, s38, 6, v9
	s_lshl_b32 s31, s38, 13
	v_lshl_or_b32 v9, v9, 6, v187
	v_and_b32_e32 v10, 32, v10
	v_lshl_or_b32 v2, v3, 6, v2
	v_bitop3_b32 v11, v9, s31, v10 bitop3:0xde
	s_lshl_b32 s31, s39, 12
	v_lshl_add_u32 v166, v5, 1, v2
	v_lshlrev_b32_e32 v2, 13, v6
	s_cmpk_lt_u32 s30, 0x100
	v_and_b32_e32 v2, 0xffffc000, v2
	v_bitop3_b32 v189, v9, s31, v10 bitop3:0xde
	s_waitcnt vmcnt(6)
	s_cselect_b64 s[30:31], -1, 0
	s_lshl_b32 s38, s38, 15
	s_lshl_b32 s39, s39, 13
	v_lshl_add_u32 v2, v7, 10, v2
	v_and_b32_e32 v3, 1, v6
	s_or_b32 s46, s39, s38
	v_lshl_or_b32 v2, v3, 6, v2
	v_readlane_b32 s4, v252, 16
	v_readlane_b32 s40, v250, 11
	s_ashr_i32 s47, s46, 31
	v_mov_b32_e32 v165, v27
	v_mov_b32_e32 v167, v27
	v_lshl_add_u32 v176, v8, 1, v2
	v_mov_b32_e32 v177, v27
	s_mov_b64 s[60:61], 0
	v_add_u32_e32 v190, 0, v11
	s_mov_b32 s58, s4
	v_readlane_b32 s41, v250, 12
	v_readlane_b32 s59, v252, 17
	s_mov_b64 s[78:79], s[70:71]
	s_mov_b64 s[76:77], s[36:37]
	s_barrier
	s_branch .LBB0_205

.LBB0_377:
	v_mov_b32_e32 v159, v27
	v_lshl_add_u64 v[2:3], s[20:21], 0, v[158:159]
	v_mov_b32_e32 v163, v27
	v_readlane_b32 s52, v253, 57
	v_lshl_add_u64 v[4:5], s[20:21], 0, v[162:163]
	v_mov_b32_e32 v157, v27
	v_readlane_b32 s53, v253, 58
	s_and_b32 s1, s1, 3
	s_add_i32 m0, s11, 0x18000
	v_lshl_add_u64 v[2:3], v[2:3], 0, s[82:83]
	v_lshl_add_u64 v[14:15], s[52:53], 0, v[156:157]
	v_mov_b32_e32 v161, v27
	s_lshl_b32 s12, s27, 13
	s_lshl_b32 s34, s1, 12
	global_load_lds_dwordx4 v[2:3], off
	v_lshl_add_u64 v[2:3], v[4:5], 0, s[82:83]
	s_add_i32 m0, s11, 0x1a000
	s_add_i32 s23, s11, 0x8000
	s_add_i32 s26, s11, 0xa000
	v_lshl_add_u64 v[16:17], s[52:53], 0, v[160:161]
	global_load_lds_dwordx4 v[2:3], off
	v_lshl_add_u64 v[2:3], v[14:15], 0, s[82:83]
	s_mov_b32 m0, s23
	s_add_u32 s30, s20, 0x20080
	global_load_lds_dwordx4 v[2:3], off
	v_lshl_add_u64 v[2:3], v[16:17], 0, s[82:83]
	s_mov_b32 m0, s26
	s_addc_u32 s31, s21, 0
	global_load_lds_dwordx4 v[2:3], off
	s_add_i32 m0, s11, 0x1c000
	v_lshl_add_u64 v[2:3], s[30:31], 0, v[158:159]
	global_load_lds_dwordx4 v[2:3], off
	v_lshl_add_u64 v[2:3], s[30:31], 0, v[162:163]
	s_add_i32 m0, s11, 0x1e000
	v_and_b32_e32 v188, 48, v6
	global_load_lds_dwordx4 v[2:3], off
	s_waitcnt vmcnt(8)
	s_barrier
	v_and_b32_e32 v2, 15, v6
	v_lshlrev_b32_e32 v3, 2, v6
	v_lshl_or_b32 v189, s27, 6, v2
	v_lshl_or_b32 v2, v2, 6, v188
	v_and_b32_e32 v3, 32, v3
	v_bitop3_b32 v4, v2, s12, v3 bitop3:0xde
	v_bitop3_b32 v190, v2, s34, v3 bitop3:0xde
	v_lshlrev_b32_e32 v2, 3, v6
	v_and_b32_e32 v164, 0x1f8, v2
	v_lshlrev_b32_e32 v2, 13, v7
	v_and_b32_e32 v2, 0xffffc000, v2
	v_lshl_add_u32 v2, v8, 10, v2
	v_and_b32_e32 v3, 1, v7
	v_lshl_or_b32 v2, v3, 6, v2
	v_lshl_add_u32 v166, v9, 1, v2
	v_lshlrev_b32_e32 v2, 13, v10
	s_cmpk_lt_u32 s0, 0x100
	v_and_b32_e32 v2, 0xffffc000, v2
	s_waitcnt vmcnt(6)
	s_cselect_b64 s[30:31], -1, 0
	s_lshl_b32 s0, s27, 15
	s_lshl_b32 s1, s1, 13
	v_lshl_add_u32 v2, v11, 10, v2
	v_and_b32_e32 v3, 1, v10
	s_or_b32 s27, s1, s0
	v_lshl_or_b32 v2, v3, 6, v2
	v_readlane_b32 s0, v253, 51
	s_ashr_i32 s46, s27, 31
	v_mov_b32_e32 v165, v27
	v_mov_b32_e32 v167, v27
	v_lshl_add_u32 v176, v12, 1, v2
	v_mov_b32_e32 v177, v27
	s_mov_b64 s[36:37], -1
	v_add_u32_e32 v191, 0, v4
	s_mov_b32 s34, s0
	s_barrier
	s_branch .LBB0_380

.LBB0_491:
	v_lshl_add_u64 v[2:3], s[0:1], 0, v[26:27]
	v_mov_b32_e32 v161, v27
	v_and_b32_e32 v16, 15, v182
	v_and_b32_e32 v184, 48, v182
	v_lshlrev_b32_e32 v17, 2, v182
	v_lshl_add_u64 v[4:5], s[0:1], 0, v[160:161]
	v_mov_b32_e32 v157, v27
	s_and_b32 s27, s20, 3
	v_lshl_or_b32 v185, s11, 6, v16
	s_lshl_b32 s12, s11, 13
	v_lshl_or_b32 v16, v16, 6, v184
	v_and_b32_e32 v17, 32, v17
	s_add_i32 m0, s17, 0x18000
	v_lshl_add_u64 v[2:3], v[2:3], 0, s[82:83]
	v_lshl_add_u64 v[12:13], s[84:85], 0, v[156:157]
	v_mov_b32_e32 v159, v27
	v_bitop3_b32 v18, v16, s12, v17 bitop3:0xde
	s_lshl_b32 s12, s27, 12
	global_load_lds_dwordx4 v[2:3], off
	v_lshl_add_u64 v[2:3], v[4:5], 0, s[82:83]
	s_add_i32 m0, s17, 0x1a000
	s_add_i32 s34, s17, 0x8000
	s_add_i32 s35, s17, 0xa000
	v_lshl_add_u64 v[14:15], s[84:85], 0, v[158:159]
	global_load_lds_dwordx4 v[2:3], off
	v_lshl_add_u64 v[2:3], v[12:13], 0, s[82:83]
	s_mov_b32 m0, s34
	s_add_u32 s20, s0, 0x20080
	global_load_lds_dwordx4 v[2:3], off
	v_lshl_add_u64 v[2:3], v[14:15], 0, s[82:83]
	s_mov_b32 m0, s35
	s_addc_u32 s21, s1, 0
	global_load_lds_dwordx4 v[2:3], off
	s_add_i32 m0, s17, 0x1c000
	v_lshl_add_u64 v[2:3], s[20:21], 0, v[26:27]
	global_load_lds_dwordx4 v[2:3], off
	v_lshl_add_u64 v[2:3], s[20:21], 0, v[160:161]
	s_add_i32 m0, s17, 0x1e000
	v_readlane_b32 s4, v251, 61
	global_load_lds_dwordx4 v[2:3], off
	s_waitcnt vmcnt(8)
	s_barrier
	v_lshlrev_b32_e32 v2, 13, v6
	v_and_b32_e32 v2, 0xffffc000, v2
	v_lshl_add_u32 v2, v7, 10, v2
	v_and_b32_e32 v3, 1, v6
	v_lshl_or_b32 v2, v3, 6, v2
	v_lshl_add_u32 v2, v8, 1, v2
	v_mov_b32_e32 v3, v27
	v_readlane_b32 s5, v251, 62
	s_waitcnt vmcnt(6)
	v_bitop3_b32 v186, v16, s12, v17 bitop3:0xde
	s_mov_b32 s36, -2
	v_lshl_add_u64 v[162:163], s[4:5], 0, v[2:3]
	v_lshlrev_b32_e32 v2, 13, v9
	v_and_b32_e32 v2, 0xffffc000, v2
	v_lshl_add_u32 v2, v10, 10, v2
	v_and_b32_e32 v3, 1, v9
	v_lshl_or_b32 v2, v3, 6, v2
	v_lshl_add_u32 v2, v11, 1, v2
	v_mov_b32_e32 v3, v27
	v_lshl_add_u64 v[164:165], s[4:5], 0, v[2:3]
	s_mov_b64 s[20:21], 0xd220080
	v_add_u32_e32 v187, 0, v18
	s_barrier

.LBB0_542:
	s_and_b32 s1, s1, 3
	s_add_i32 m0, s16, 0x18000
	v_lshl_add_u64 v[146:147], v[146:147], 0, s[82:83]
	s_lshl_b32 s12, s34, 13
	s_lshl_b32 s35, s1, 12
	global_load_lds_dwordx4 v[146:147], off
	v_lshl_add_u64 v[144:145], v[144:145], 0, s[82:83]
	s_add_i32 m0, s16, 0x1a000
	s_add_i32 s26, s16, 0x8000
	s_add_i32 s27, s16, 0xa000
	global_load_lds_dwordx4 v[144:145], off
	v_lshl_add_u64 v[140:141], v[140:141], 0, s[82:83]
	s_mov_b32 m0, s26
	s_add_u32 s30, s58, 0x60080
	global_load_lds_dwordx4 v[140:141], off
	v_lshl_add_u64 v[140:141], v[142:143], 0, s[82:83]
	s_mov_b32 m0, s27
	s_addc_u32 s31, s59, 0
	global_load_lds_dwordx4 v[140:141], off
	s_add_i32 m0, s16, 0x1c000
	v_lshl_add_u64 v[140:141], s[30:31], 0, v[134:135]
	global_load_lds_dwordx4 v[140:141], off
	v_lshl_add_u64 v[140:141], s[30:31], 0, v[138:139]
	s_add_i32 m0, s16, 0x1e000
	v_lshlrev_b32_e32 v144, 2, v149
	global_load_lds_dwordx4 v[140:141], off
	s_waitcnt vmcnt(8)
	s_barrier
	v_bfe_u32 v141, v149, 4, 2
	v_and_b32_e32 v140, 15, v149
	v_lshlrev_b32_e32 v142, 4, v141
	v_lshl_or_b32 v143, v140, 6, v142
	v_and_b32_e32 v144, 32, v144
	s_cmpk_lt_u32 s0, 0x100
	v_bitop3_b32 v146, v143, s12, v144 bitop3:0xde
	s_cselect_b64 s[30:31], -1, 0
	s_lshl_b32 s0, s34, 15
	s_lshl_b32 s12, s1, 13
	v_lshl_or_b32 v228, s1, 6, v142
	v_lshrrev_b32_e32 v142, 1, v148
	v_mul_lo_u32 v26, v26, s7
	s_mov_b32 s4, 0x2c000
	v_bitop3_b32 v227, v143, s35, v144 bitop3:0xde
	s_or_b32 s46, s12, s0
	v_mad_u64_u32 v[142:143], s[0:1], v142, s4, v[26:27]
	v_and_b32_e32 v26, 1, v148
	v_lshl_or_b32 v26, v26, 6, v142
	v_lshl_add_u32 v142, v150, 1, v26
	v_lshrrev_b32_e32 v144, 1, v151
	v_mul_lo_u32 v26, v152, s7
	s_waitcnt vmcnt(6)
	v_mad_u64_u32 v[144:145], s[0:1], v144, s4, v[26:27]
	v_and_b32_e32 v26, 1, v151
	v_lshl_or_b32 v226, s34, 6, v140
	v_lshlrev_b32_e32 v140, 3, v140
	v_lshl_or_b32 v26, v26, 6, v144
	s_ashr_i32 s47, s46, 31
	v_lshl_or_b32 v140, v141, 7, v140
	v_mov_b32_e32 v141, v27
	s_mul_hi_i32 s68, s13, 0x160000
	s_mul_i32 s74, s13, 0x160000
	s_mul_hi_i32 s75, s56, 0x60000
	s_mul_i32 s76, s56, 0x60000
	v_mov_b32_e32 v143, v27
	v_lshl_add_u32 v144, v153, 1, v26
	v_mov_b32_e32 v145, v27
	s_mov_b32 s0, 0
	v_add_u32_e32 v229, 0, v146
	s_mov_b32 s79, 0
	s_barrier
	s_branch .LBB0_545

.LBB0_668:
	s_and_b32 s12, s1, 3
	s_add_i32 m0, s11, 0x18000
	v_lshl_add_u64 v[138:139], v[138:139], 0, s[82:83]
	s_lshl_b32 s1, s30, 13
	s_lshl_b32 s31, s12, 12
	global_load_lds_dwordx4 v[138:139], off
	v_lshl_add_u64 v[136:137], v[136:137], 0, s[82:83]
	s_add_i32 m0, s11, 0x1a000
	s_add_i32 s46, s11, 0x8000
	s_add_i32 s47, s11, 0xa000
	global_load_lds_dwordx4 v[136:137], off
	v_lshl_add_u64 v[132:133], v[132:133], 0, s[82:83]
	s_mov_b32 m0, s46
	s_add_u32 s26, s74, 0x40080
	global_load_lds_dwordx4 v[132:133], off
	v_lshl_add_u64 v[132:133], v[134:135], 0, s[82:83]
	s_mov_b32 m0, s47
	s_addc_u32 s27, s75, 0
	global_load_lds_dwordx4 v[132:133], off
	s_add_i32 m0, s11, 0x1c000
	v_lshl_add_u64 v[132:133], s[26:27], 0, v[178:179]
	global_load_lds_dwordx4 v[132:133], off
	v_lshl_add_u64 v[132:133], s[26:27], 0, v[182:183]
	s_add_i32 m0, s11, 0x1e000
	v_lshlrev_b32_e32 v135, 2, v140
	global_load_lds_dwordx4 v[132:133], off
	s_waitcnt vmcnt(8)
	s_barrier
	v_bfe_u32 v133, v140, 4, 2
	v_and_b32_e32 v132, 15, v140
	v_lshlrev_b32_e32 v201, 4, v133
	v_lshl_or_b32 v200, s30, 6, v132
	v_lshl_or_b32 v132, v132, 6, v201
	v_and_b32_e32 v135, 32, v135
	v_bitop3_b32 v136, v132, s1, v135 bitop3:0xde
	v_bitop3_b32 v202, v132, s31, v135 bitop3:0xde
	v_lshrrev_b32_e32 v132, 1, v141
	v_mul_lo_u32 v26, v26, s7
	s_mov_b32 s5, 0x2c000
	v_lshlrev_b32_e32 v134, 3, v133
	s_cmpk_lt_u32 s0, 0x100
	v_cmp_eq_u32_e64 s[0:1], 0, v133
	v_mad_u64_u32 v[132:133], s[34:35], v132, s5, v[26:27]
	v_and_b32_e32 v26, 1, v141
	v_lshl_or_b32 v26, v26, 6, v132
	v_lshl_add_u32 v188, v142, 1, v26
	v_lshrrev_b32_e32 v132, 1, v143
	v_mul_lo_u32 v26, v144, s7
	s_waitcnt vmcnt(6)
	s_cselect_b64 s[26:27], -1, 0
	v_lshl_or_b32 v203, s12, 5, v134
	s_or_b32 s30, s12, s30
	v_mad_u64_u32 v[132:133], s[34:35], v132, s5, v[26:27]
	v_and_b32_e32 v26, 1, v143
	s_cmp_eq_u32 s30, 0
	v_lshlrev_b32_e32 v184, 2, v203
	v_mov_b32_e32 v185, v27
	v_lshl_or_b32 v26, v26, 6, v132
	s_mov_b32 s57, 0
	s_cselect_b64 s[30:31], -1, 0
	v_lshl_add_u64 v[186:187], s[48:49], 0, v[184:185]
	v_mov_b32_e32 v189, v27
	v_lshl_add_u32 v190, v145, 1, v26
	v_mov_b32_e32 v191, v27
	v_add_u32_e32 v185, 0, v136
	s_lshl_b32 s68, s12, 2
	s_barrier
	s_branch .LBB0_671

.LBB0_727:
	s_and_b32 s12, s1, 3
	s_add_i32 m0, s11, 0x18000
	v_lshl_add_u64 v[138:139], v[138:139], 0, s[82:83]
	s_lshl_b32 s1, s26, 13
	s_lshl_b32 s27, s12, 12
	global_load_lds_dwordx4 v[138:139], off
	v_lshl_add_u64 v[136:137], v[136:137], 0, s[82:83]
	s_add_i32 m0, s11, 0x1a000
	s_add_i32 s46, s11, 0x8000
	s_add_i32 s47, s11, 0xa000
	global_load_lds_dwordx4 v[136:137], off
	v_lshl_add_u64 v[132:133], v[132:133], 0, s[82:83]
	s_mov_b32 m0, s46
	s_add_u32 s30, s58, 0x40080
	global_load_lds_dwordx4 v[132:133], off
	v_lshl_add_u64 v[132:133], v[134:135], 0, s[82:83]
	s_mov_b32 m0, s47
	s_addc_u32 s31, s59, 0
	global_load_lds_dwordx4 v[132:133], off
	s_add_i32 m0, s11, 0x1c000
	v_lshl_add_u64 v[132:133], s[30:31], 0, v[146:147]
	global_load_lds_dwordx4 v[132:133], off
	v_lshl_add_u64 v[132:133], s[30:31], 0, v[150:151]
	s_add_i32 m0, s11, 0x1e000
	v_mul_lo_u32 v26, v26, s7
	global_load_lds_dwordx4 v[132:133], off
	s_waitcnt vmcnt(8)
	s_barrier
	v_bfe_u32 v133, v140, 4, 2
	v_and_b32_e32 v132, 15, v140
	v_lshlrev_b32_e32 v135, 4, v133
	v_lshl_or_b32 v164, s26, 6, v132
	v_lshl_or_b32 v132, v132, 6, v135
	v_lshlrev_b32_e32 v135, 2, v140
	v_and_b32_e32 v135, 32, v135
	v_bitop3_b32 v136, v132, s1, v135 bitop3:0xde
	v_bitop3_b32 v165, v132, s27, v135 bitop3:0xde
	v_lshrrev_b32_e32 v132, 1, v141
	s_mov_b32 s4, 0x2c000
	v_lshlrev_b32_e32 v134, 3, v133
	s_cmpk_lt_u32 s0, 0x100
	v_cmp_eq_u32_e64 s[0:1], 0, v133
	v_mad_u64_u32 v[132:133], s[30:31], v132, s4, v[26:27]
	v_and_b32_e32 v26, 1, v141
	v_lshl_or_b32 v26, v26, 6, v132
	v_lshl_add_u32 v152, v142, 1, v26
	v_lshrrev_b32_e32 v132, 1, v143
	v_mul_lo_u32 v26, v154, s7
	s_waitcnt vmcnt(6)
	v_mad_u64_u32 v[132:133], s[30:31], v132, s4, v[26:27]
	v_and_b32_e32 v26, 1, v143
	v_lshl_or_b32 v26, v26, 6, v132
	s_cselect_b64 s[26:27], -1, 0
	v_lshl_or_b32 v166, s12, 5, v134
	s_mov_b32 s57, 0
	v_mov_b32_e32 v153, v27
	v_lshl_add_u32 v154, v155, 1, v26
	v_mov_b32_e32 v155, v27
	v_add_u32_e32 v167, 0, v136
	s_lshl_b32 s68, s12, 2
	s_barrier
	s_branch .LBB0_730
